# two-level barrier: the acquire's buffer_inv sc1 issued at arrival (overlaps the wait; only sc1 polls follow) instead of after the poll
# speedup vs baseline: 1.0054x; 1.0054x over previous
.LBB0_690:
	s_waitcnt vmcnt(0) lgkmcnt(0)
	s_waitcnt lgkmcnt(0)
	s_barrier
	s_mov_b64 s[2:3], exec
	v_readlane_b32 s4, v254, 58
	v_readlane_b32 s5, v254, 59
	s_and_b64 s[4:5], s[2:3], s[4:5]
	v_readlane_b32 s33, v254, 30
	v_readlane_b32 s36, v254, 31
	s_mov_b64 exec, s[4:5]
	s_cbranch_execz .LBB0_696
	s_mov_b64 s[4:5], exec
	v_readlane_b32 s4, v255, 31
	s_add_i32 s4, s4, 1
	s_add_i32 s4, s4, -1
	v_readlane_b32 s5, v255, 51
	s_lshl_b32 s5, s5, 6
	s_add_i32 s5, s5, 0x200
	v_mov_b32_e32 v1, s5
	v_mov_b32_e32 v2, 1
	global_atomic_add v3, v1, v2, s[44:45] sc0
	buffer_inv sc1
	v_readlane_b32 s6, v255, 52
	s_mul_i32 s6, s6, s4
	s_waitcnt vmcnt(0)
	v_readfirstlane_b32 s7, v3
	s_add_i32 s7, s7, 1
	s_cmp_lg_u32 s7, s6
	s_cbranch_scc1 .Lhb1_nl
	buffer_wbl2 sc1
	s_waitcnt vmcnt(0)
	global_atomic_add v211, v2, s[44:45] offset:256

.Lhb1_poll:
	global_load_dword v1, v211, s[44:45] offset:256 sc1
	s_waitcnt vmcnt(0)
	v_cmp_gt_u32_e32 vcc, s4, v1
	s_cbranch_vccz .Lhb1_done
	s_sleep 3
	s_add_i32 s5, s5, 1
	s_cmp_lt_u32 s5, 0x20000
	s_cbranch_scc1 .Lhb1_poll
.Lhb1_done:
	s_waitcnt vmcnt(0)
.LBB0_696:
	s_or_b64 exec, exec, s[2:3]
	v_readlane_b32 s4, v255, 33
	v_readlane_b32 s5, v255, 34
	s_xor_b64 s[2:3], s[4:5], -1
	v_writelane_b32 v255, s2, 35
	s_lshl_b32 s58, s30, 4
	s_mov_b32 s10, s30
	v_writelane_b32 v255, s3, 36
	s_lshl_b64 s[2:3], s[58:59], 2
	s_add_u32 s2, s44, s2
	s_addc_u32 s3, s45, s3
	v_writelane_b32 v255, s2, 37
	s_mul_i32 s58, s30, 0x300
	s_mov_b32 s11, s59
	v_writelane_b32 v255, s3, 38
	s_and_b64 s[2:3], s[4:5], exec
	s_cselect_b32 s94, 64, 0
	s_cselect_b32 s53, 16, 0
	s_movk_i32 s3, 0x900
	s_cselect_b32 s2, 32, 0
	s_cselect_b32 s3, s3, 0x800
	s_or_b32 s4, s94, s53
	s_or_b32 s4, s4, s2
	s_bitset1_b32 s2, 8
	v_writelane_b32 v255, s2, 39
	s_lshl_b32 s2, s30, 2
	s_or_b32 s6, s4, s3
	v_writelane_b32 v255, s2, 40
	s_addk_i32 s6, 0x350
	s_lshl_b64 s[2:3], s[58:59], 2
	v_readlane_b32 s4, v255, 0
	s_add_u32 s4, s4, s2
	v_readlane_b32 s2, v255, 1
	s_addc_u32 s5, s2, s3
	v_writelane_b32 v255, s4, 41
	s_lshl_b64 s[2:3], s[10:11], 2
	v_mov_b32_e32 v228, 0x8f
	v_writelane_b32 v255, s5, 42
	v_readlane_b32 s4, v254, 16
	v_readlane_b32 s5, v254, 17
	s_add_u32 s4, s4, s2
	s_addc_u32 s5, s5, s3
	v_writelane_b32 v255, s4, 43
	s_barrier
	s_nop 0
	v_writelane_b32 v255, s5, 44
	s_nop 0
	v_readlane_b32 s4, v255, 23
	s_add_u32 s4, s4, s2
	v_readlane_b32 s2, v255, 24
	s_addc_u32 s5, s2, s3
	v_writelane_b32 v255, s4, 45
	s_nop 1
	v_writelane_b32 v255, s5, 46
	v_writelane_b32 v255, s10, 47
	s_lshl_b32 s58, s10, 6
	s_lshl_b64 s[2:3], s[58:59], 2
	v_writelane_b32 v255, s11, 48
	s_nop 0
	v_readlane_b32 s4, v255, 2
	s_add_u32 s34, s4, s2
	v_readlane_b32 s2, v255, 3
	s_addc_u32 s35, s2, s3
	s_branch .LBB0_700

.LBB0_991:
	s_waitcnt vmcnt(0) lgkmcnt(0)
	s_waitcnt vmcnt(63) expcnt(7) lgkmcnt(15)
	s_barrier
	s_mov_b64 s[2:3], exec
	v_readlane_b32 s4, v254, 58
	v_readlane_b32 s5, v254, 59
	v_readlane_b32 s12, v255, 33
	s_and_b64 s[4:5], s[2:3], s[4:5]
	v_readlane_b32 s13, v255, 34
	s_mov_b64 exec, s[4:5]
	s_cbranch_execz .LBB0_997
	s_mov_b64 s[4:5], exec
	v_readlane_b32 s4, v255, 31
	s_add_i32 s4, s4, 2
	s_add_i32 s4, s4, -1
	v_readlane_b32 s5, v255, 51
	s_lshl_b32 s5, s5, 6
	s_add_i32 s5, s5, 0x200
	v_mov_b32_e32 v1, s5
	v_mov_b32_e32 v2, 1
	global_atomic_add v3, v1, v2, s[44:45] sc0
	buffer_inv sc1
	v_readlane_b32 s6, v255, 52
	s_mul_i32 s6, s6, s4
	s_waitcnt vmcnt(0)
	v_readfirstlane_b32 s7, v3
	s_add_i32 s7, s7, 1
	s_cmp_lg_u32 s7, s6
	s_cbranch_scc1 .Lhb2_nl
	buffer_wbl2 sc1
	s_waitcnt vmcnt(0)
	global_atomic_add v211, v2, s[44:45] offset:256

.Lhb2_poll:
	global_load_dword v1, v211, s[44:45] offset:256 sc1
	s_waitcnt vmcnt(0)
	v_cmp_gt_u32_e32 vcc, s4, v1
	s_cbranch_vccz .Lhb2_done
	s_sleep 3
	s_add_i32 s5, s5, 1
	s_cmp_lt_u32 s5, 0x20000
	s_cbranch_scc1 .Lhb2_poll
.Lhb2_done:
	s_waitcnt vmcnt(0)
.LBB0_997:
	s_or_b64 exec, exec, s[2:3]
	s_and_b64 s[2:3], s[12:13], exec
	s_mov_b32 s2, 0x9000
	s_cselect_b32 s6, s2, 0x8000
	s_lshr_b32 s9, s6, 8
	s_lshr_b32 s53, s6, 6
	v_readlane_b32 s2, v255, 22
	s_cmp_lt_i32 s2, s53
	s_cselect_b64 s[4:5], -1, 0
	v_writelane_b32 v255, s4, 37
	s_cmp_ge_i32 s2, s53
	v_mov_b32_e32 v212, v228
	v_writelane_b32 v255, s5, 38
	s_nop 0
	v_readlane_b32 s2, v255, 47
	s_mul_i32 s54, s2, 17
	s_barrier
	v_readlane_b32 s3, v255, 48
	s_cbranch_scc1 .LBB0_1065
	v_readlane_b32 s4, v255, 47
	s_lshl_b32 s2, s4, 21
	v_readlane_b32 s3, v254, 22
	s_add_u32 s7, s3, s2
	v_readlane_b32 s2, v254, 23
	s_addc_u32 s28, s2, 0
	v_readlane_b32 s2, v255, 33
	v_readlane_b32 s3, v255, 34
	s_and_b64 s[2:3], s[2:3], exec
	v_readlane_b32 s12, v254, 37
	v_readlane_b32 s2, v254, 55
	v_readlane_b32 s36, v254, 0
	v_readlane_b32 s16, v254, 41
	v_readlane_b32 s17, v254, 42
	v_readlane_b32 s18, v254, 43
	v_readlane_b32 s19, v254, 44
	v_readlane_b32 s3, v254, 56
	v_readlane_b32 s48, v254, 12
	v_readlane_b32 s49, v254, 13
	v_readlane_b32 s5, v255, 48
	v_readlane_b32 s13, v254, 38
	s_cselect_b32 s11, s17, s3
	s_cselect_b32 s10, s16, s2
	v_readlane_b32 s50, v254, 14
	v_readlane_b32 s51, v254, 15
	s_mov_b64 s[16:17], s[48:49]
	v_readlane_b32 s14, v254, 39
	s_mov_b64 s[18:19], s[50:51]
	s_cselect_b32 s13, s13, s17
	s_cselect_b32 s12, s12, s16
	s_lshl_b64 s[2:3], s[4:5], 21
	v_readlane_b32 s15, v254, 40
	s_add_u32 s14, s18, s2
	s_addc_u32 s15, s19, s3
	v_readlane_b32 s29, v255, 22
	v_readlane_b32 s20, v254, 45
	v_readlane_b32 s21, v254, 46
	v_readlane_b32 s22, v254, 47
	v_readlane_b32 s23, v254, 48
	v_readlane_b32 s24, v254, 49
	v_readlane_b32 s25, v254, 50
	v_readlane_b32 s26, v254, 51
	v_readlane_b32 s27, v254, 52
	v_readlane_b32 s37, v254, 1
	v_readlane_b32 s38, v254, 2
	v_readlane_b32 s39, v254, 3
	v_readlane_b32 s40, v254, 4
	v_readlane_b32 s41, v254, 5
	v_readlane_b32 s42, v254, 6
	v_readlane_b32 s43, v254, 7
	v_readlane_b32 s44, v254, 8
	v_readlane_b32 s45, v254, 9
	v_readlane_b32 s46, v254, 10
	v_readlane_b32 s47, v254, 11
	s_branch .LBB0_1000

.LBB0_1065:
	s_waitcnt vmcnt(0) lgkmcnt(0)
	s_barrier
	s_mov_b64 s[2:3], exec
	v_readlane_b32 s4, v254, 58
	v_readlane_b32 s5, v254, 59
	s_and_b64 s[4:5], s[2:3], s[4:5]
	s_mov_b64 exec, s[4:5]
	s_cbranch_execz .LBB0_1071
	s_mov_b64 s[4:5], exec
	v_readlane_b32 s4, v255, 31
	s_add_i32 s4, s4, 3
	s_add_i32 s4, s4, -1
	v_readlane_b32 s5, v255, 51
	s_lshl_b32 s5, s5, 6
	s_add_i32 s5, s5, 0x200
	v_mov_b32_e32 v1, s5
	v_mov_b32_e32 v2, 1
	global_atomic_add v3, v1, v2, s[44:45] sc0
	buffer_inv sc1
	v_readlane_b32 s10, v255, 52
	s_mul_i32 s10, s10, s4
	s_waitcnt vmcnt(0)
	v_readfirstlane_b32 s11, v3
	s_add_i32 s11, s11, 1
	s_cmp_lg_u32 s11, s10
	s_cbranch_scc1 .Lhb3_nl
	buffer_wbl2 sc1
	s_waitcnt vmcnt(0)
	global_atomic_add v211, v2, s[44:45] offset:256

.Lhb3_poll:
	global_load_dword v1, v211, s[44:45] offset:256 sc1
	s_waitcnt vmcnt(0)
	v_cmp_gt_u32_e32 vcc, s4, v1
	s_cbranch_vccz .Lhb3_done
	s_sleep 3
	s_add_i32 s5, s5, 1
	s_cmp_lt_u32 s5, 0x20000
	s_cbranch_scc1 .Lhb3_poll
.Lhb3_done:
	s_waitcnt vmcnt(0)
.LBB0_1071:
	s_or_b64 exec, exec, s[2:3]
	v_mov_b32_e32 v1, v222
	s_barrier
	v_readlane_b32 s2, v254, 57
	v_ashrrev_i32_e32 v2, 6, v1
	s_nop 0
	v_add_u32_e32 v18, s2, v2
	v_cmp_gt_i32_e32 vcc, s6, v18
	s_and_saveexec_b64 s[2:3], vcc
	s_cbranch_execz .LBB0_1078
	v_readfirstlane_b32 s7, v18
	v_mbcnt_lo_u32_b32 v10, -1, 0
	v_mbcnt_hi_u32_b32 v10, -1, v10
	v_lshlrev_b32_e32 v2, 4, v10
	v_lshlrev_b32_e32 v3, 3, v10
	v_xor_b32_e32 v4, 32, v10
	v_lshlrev_b32_e32 v4, 2, v4
	v_xor_b32_e32 v5, 16, v10
	v_lshlrev_b32_e32 v5, 2, v5
	v_xor_b32_e32 v6, 8, v10
	v_lshlrev_b32_e32 v6, 2, v6
	v_xor_b32_e32 v7, 4, v10
	v_lshlrev_b32_e32 v7, 2, v7
	v_xor_b32_e32 v8, 2, v10
	v_lshlrev_b32_e32 v8, 2, v8
	v_xor_b32_e32 v9, 1, v10
	v_lshlrev_b32_e32 v9, 2, v9
	v_mov_b32_e32 v16, 0x358637bd
	v_readlane_b32 s22, v254, 12
	v_readlane_b32 s23, v254, 13
	v_readlane_b32 s24, v254, 55
	v_readlane_b32 s25, v254, 56
	v_readlane_b32 s20, v254, 14
	v_readlane_b32 s21, v254, 15
	v_readlane_b32 s18, v254, 60
	v_readlane_b32 s19, v254, 61
	v_readlane_b32 s5, v255, 47
	s_lshl_b32 s5, s5, 12
	s_add_u32 s18, s18, s5
	s_addc_u32 s19, s19, 0
	s_nop 4
	global_load_dwordx4 v[136:139], v2, s[18:19] offset:0
	global_load_dwordx4 v[140:143], v2, s[18:19] offset:1024
	global_load_dwordx4 v[144:147], v2, s[18:19] offset:2048
	global_load_dwordx4 v[148:151], v2, s[18:19] offset:3072
	s_cmp_lt_u32 s7, 0x8000
	s_cselect_b32 s10, s22, s24
	s_cselect_b32 s11, s23, s25
	s_cselect_b32 s5, s7, 0x8000
	s_and_b32 s26, s7, 0x7fff
	s_lshl_b32 s27, s26, 12
	s_lshr_b32 s26, s26, 20
	s_add_u32 s10, s10, s27
	s_addc_u32 s11, s11, s26
	s_lshr_b32 s5, s5, 11
	s_add_i32 s5, s5, s54
	s_mul_i32 s5, s5, 0x6000
	s_add_u32 s14, s20, s5
	s_addc_u32 s15, s21, 0
	s_add_u32 s16, s14, 0x3000
	s_addc_u32 s17, s15, 0
	s_add_u32 s14, s14, 0x4000
	s_addc_u32 s15, s15, 0
	global_load_dwordx4 v[40:43], v2, s[10:11] offset:0
	global_load_dwordx4 v[44:47], v2, s[10:11] offset:1024
	global_load_dwordx4 v[48:51], v2, s[10:11] offset:2048
	global_load_dwordx4 v[52:55], v2, s[10:11] offset:3072
	global_load_dwordx4 v[56:59], v2, s[14:15] offset:0
	global_load_dwordx4 v[60:63], v2, s[14:15] offset:1024
	global_load_dwordx4 v[64:67], v2, s[14:15] offset:2048
	global_load_dwordx4 v[68:71], v2, s[14:15] offset:3072
	global_load_dwordx4 v[72:75], v2, s[16:17] offset:0
	global_load_dwordx4 v[76:79], v2, s[16:17] offset:1024
	global_load_dwordx4 v[80:83], v2, s[16:17] offset:2048
	global_load_dwordx4 v[84:87], v2, s[16:17] offset:3072
	s_waitcnt vmcnt(0)

.LBB0_1078:
	s_or_b64 exec, exec, s[2:3]
	s_waitcnt vmcnt(0) lgkmcnt(0)
	s_barrier
	s_mov_b64 s[2:3], exec
	v_readlane_b32 s4, v254, 58
	v_readlane_b32 s5, v254, 59
	s_and_b64 s[4:5], s[2:3], s[4:5]
	s_mov_b64 exec, s[4:5]
	s_cbranch_execz .LBB0_1084
	s_mov_b64 s[4:5], exec
	v_readlane_b32 s4, v255, 31
	s_add_i32 s4, s4, 4
	s_add_i32 s4, s4, -1
	v_readlane_b32 s5, v255, 51
	s_lshl_b32 s5, s5, 6
	s_add_i32 s5, s5, 0x200
	v_mov_b32_e32 v1, s5
	v_mov_b32_e32 v2, 1
	global_atomic_add v3, v1, v2, s[44:45] sc0
	buffer_inv sc1
	v_readlane_b32 s10, v255, 52
	s_mul_i32 s10, s10, s4
	s_waitcnt vmcnt(0)
	v_readfirstlane_b32 s11, v3
	s_add_i32 s11, s11, 1
	s_cmp_lg_u32 s11, s10
	s_cbranch_scc1 .Lhb4_nl
	buffer_wbl2 sc1
	s_waitcnt vmcnt(0)
	global_atomic_add v211, v2, s[44:45] offset:256

.Lhb4_poll:
	global_load_dword v1, v211, s[44:45] offset:256 sc1
	s_waitcnt vmcnt(0)
	v_cmp_gt_u32_e32 vcc, s4, v1
	s_cbranch_vccz .Lhb4_done
	s_sleep 3
	s_add_i32 s5, s5, 1
	s_cmp_lt_u32 s5, 0x20000
	s_cbranch_scc1 .Lhb4_poll
.Lhb4_done:
	s_waitcnt vmcnt(0)
.LBB0_1084:
	s_or_b64 exec, exec, s[2:3]
	s_or_b32 s2, s6, 0xfc
	s_lshr_b32 s2, s2, 1
	s_mul_i32 s2, s2, 0x8103
	s_lshr_b32 s7, s2, 22
	s_mul_i32 s58, s7, 22
	v_readlane_b32 s2, v255, 22
	s_cmp_ge_i32 s2, s58
	s_barrier
	s_cbranch_scc1 .LBB0_1136
	v_readlane_b32 s2, v255, 47
	v_readlane_b32 s3, v255, 48
	s_mov_b32 s4, s2
	s_mul_i32 s2, s2, 0xb00000
	v_readlane_b32 s3, v254, 24
	s_add_u32 s55, s3, s2
	v_readlane_b32 s3, v254, 25
	s_addc_u32 s48, s3, 0
	s_mul_i32 s3, s4, 0x8400
	v_readlane_b32 s4, v255, 4
	s_add_u32 s10, s4, s3
	v_readlane_b32 s3, v255, 5
	s_addc_u32 s11, s3, 0
	s_add_u32 s12, s10, 0x2c00
	v_readlane_b32 s16, v254, 0
	s_addc_u32 s13, s11, 0
	v_readlane_b32 s17, v254, 1
	v_readlane_b32 s18, v254, 2
	v_readlane_b32 s19, v254, 3
	v_readlane_b32 s28, v254, 12
	v_readlane_b32 s29, v254, 13
	s_add_u32 s14, s10, 0x5800
	v_readlane_b32 s30, v254, 14
	v_readlane_b32 s31, v254, 15
	s_mov_b64 s[16:17], s[28:29]
	s_addc_u32 s15, s11, 0
	s_mov_b64 s[18:19], s[30:31]
	s_add_u32 s16, s18, s2
	s_addc_u32 s17, s19, 0
	v_readlane_b32 s49, v255, 22
	v_readlane_b32 s20, v254, 4
	v_readlane_b32 s21, v254, 5
	v_readlane_b32 s22, v254, 6
	v_readlane_b32 s23, v254, 7
	v_readlane_b32 s24, v254, 8
	v_readlane_b32 s25, v254, 9
	v_readlane_b32 s26, v254, 10
	v_readlane_b32 s27, v254, 11
	s_branch .LBB0_1087

.LBB0_1136:
	s_waitcnt vmcnt(0) lgkmcnt(0)
	s_barrier
	s_mov_b64 s[2:3], exec
	v_readlane_b32 s4, v254, 58
	v_readlane_b32 s5, v254, 59
	s_and_b64 s[4:5], s[2:3], s[4:5]
	s_mov_b64 exec, s[4:5]
	s_cbranch_execz .LBB0_1142
	s_mov_b64 s[4:5], exec
	v_readlane_b32 s4, v255, 31
	s_add_i32 s4, s4, 5
	s_add_i32 s4, s4, -1
	v_readlane_b32 s5, v255, 51
	s_lshl_b32 s5, s5, 6
	s_add_i32 s5, s5, 0x200
	v_mov_b32_e32 v1, s5
	v_mov_b32_e32 v2, 1
	global_atomic_add v3, v1, v2, s[44:45] sc0
	buffer_inv sc1
	v_readlane_b32 s10, v255, 52
	s_mul_i32 s10, s10, s4
	s_waitcnt vmcnt(0)
	v_readfirstlane_b32 s11, v3
	s_add_i32 s11, s11, 1
	s_cmp_lg_u32 s11, s10
	s_cbranch_scc1 .Lhb5_nl
	buffer_wbl2 sc1
	s_waitcnt vmcnt(0)
	global_atomic_add v211, v2, s[44:45] offset:256

.Lhb5_poll:
	global_load_dword v1, v211, s[44:45] offset:256 sc1
	s_waitcnt vmcnt(0)
	v_cmp_gt_u32_e32 vcc, s4, v1
	s_cbranch_vccz .Lhb5_done
	s_sleep 3
	s_add_i32 s5, s5, 1
	s_cmp_lt_u32 s5, 0x20000
	s_cbranch_scc1 .Lhb5_poll
.Lhb5_done:
	s_waitcnt vmcnt(0)
.LBB0_1142:
	s_or_b64 exec, exec, s[2:3]
	v_readlane_b32 s2, v255, 37
	v_readlane_b32 s3, v255, 38
	s_andn2_b64 vcc, exec, s[2:3]
	s_barrier
	s_cbranch_vccnz .LBB0_1178
	v_readlane_b32 s2, v255, 47
	s_mov_b64 s[24:25], s[44:45]
	v_readlane_b32 s3, v255, 48
	s_mul_i32 s58, s2, 0x2c0000
	v_readlane_b32 s36, v254, 0
	s_mov_b32 s6, s2
	s_lshl_b64 s[2:3], s[58:59], 1
	v_readlane_b32 s4, v254, 26
	v_readlane_b32 s48, v254, 12
	v_readlane_b32 s49, v254, 13
	s_add_u32 s16, s4, s2
	v_readlane_b32 s2, v254, 27
	v_readlane_b32 s50, v254, 14
	v_readlane_b32 s51, v254, 15
	s_mov_b64 s[12:13], s[48:49]
	s_addc_u32 s17, s2, s3
	s_mul_i32 s3, s6, 0x580000
	s_mov_b64 s[14:15], s[50:51]
	s_mul_hi_u32 s2, s6, 0x580000
	s_add_u32 s6, s14, s3
	s_addc_u32 s7, s15, s2
	v_readlane_b32 s18, v255, 22
	v_readlane_b32 s37, v254, 1
	v_readlane_b32 s38, v254, 2
	v_readlane_b32 s39, v254, 3
	v_readlane_b32 s40, v254, 4
	v_readlane_b32 s41, v254, 5
	v_readlane_b32 s42, v254, 6
	v_readlane_b32 s43, v254, 7
	v_readlane_b32 s44, v254, 8
	v_readlane_b32 s45, v254, 9
	v_readlane_b32 s46, v254, 10
	v_readlane_b32 s47, v254, 11
	s_branch .LBB0_1146

.LBB0_1178:
	s_waitcnt vmcnt(0) lgkmcnt(0)
	v_readlane_b32 s2, v255, 31
	s_add_i32 s9, s2, 6
	s_barrier
	s_mov_b64 s[2:3], exec
	v_readlane_b32 s4, v254, 58
	v_readlane_b32 s5, v254, 59
	s_and_b64 s[4:5], s[2:3], s[4:5]
	s_movk_i32 s39, 0x1200
	s_mov_b32 s40, 0x5040100
	s_movk_i32 s41, 0x301
	s_mov_b64 s[54:55], 0xf32e600
	s_mov_b64 exec, s[4:5]
	s_cbranch_execz .LBB0_1184
	s_mov_b64 s[4:5], exec
	s_mov_b32 s4, s9
	s_add_i32 s4, s4, -1
	v_readlane_b32 s5, v255, 51
	s_lshl_b32 s5, s5, 6
	s_add_i32 s5, s5, 0x200
	v_mov_b32_e32 v1, s5
	v_mov_b32_e32 v2, 1
	global_atomic_add v3, v1, v2, s[44:45] sc0
	buffer_inv sc1
	v_readlane_b32 s6, v255, 52
	s_mul_i32 s6, s6, s4
	s_waitcnt vmcnt(0)
	v_readfirstlane_b32 s7, v3
	s_add_i32 s7, s7, 1
	s_cmp_lg_u32 s7, s6
	s_cbranch_scc1 .Lhb6_nl
	buffer_wbl2 sc1
	s_waitcnt vmcnt(0)
	global_atomic_add v211, v2, s[44:45] offset:256

.Lhb6_poll:
	global_load_dword v1, v211, s[44:45] offset:256 sc1
	s_waitcnt vmcnt(0)
	v_cmp_gt_u32_e32 vcc, s4, v1
	s_cbranch_vccz .Lhb6_done
	s_sleep 3
	s_add_i32 s5, s5, 1
	s_cmp_lt_u32 s5, 0x20000
	s_cbranch_scc1 .Lhb6_poll
.Lhb6_done:
	s_waitcnt vmcnt(0)
.LBB0_1184:
	s_or_b64 exec, exec, s[2:3]
	v_readlane_b32 s2, v255, 33
	v_readlane_b32 s3, v255, 34
	s_andn2_b64 vcc, exec, s[2:3]
	s_barrier
	s_cbranch_vccz .LBB0_1185
	s_getpc_b64 s[98:99]
